# P0: SSM coefficient prep runs on the last 16 workgroups (which have 2 adaLN units) instead of the first 16 (3 units)
# speedup vs baseline: 1.0049x; 1.0049x over previous
.LBB0_46:
	v_writelane_b32 v240, s95, 29
	v_writelane_b32 v240, s97, 30
	s_or_b64 exec, exec, s[2:3]
	s_cmp_eq_u32 s9, 0x100
	s_cselect_b32 s0, 0x1e000, 0
	v_subrev_u32_e32 v0, s0, v0
	s_movk_i32 s0, 0x2000
	v_cmp_gt_u32_e32 vcc, s0, v0
	s_mov_b64 s[0:1], exec
	v_writelane_b32 v240, s0, 31
	s_nop 1
	v_writelane_b32 v240, s1, 32
	s_and_b64 s[0:1], s[0:1], vcc
	s_mov_b64 exec, s[0:1]
	s_cbranch_execz .LBB0_49
	s_add_u32 s0, s30, 0x40000
	s_addc_u32 s1, s31, 0
	v_writelane_b32 v240, s0, 33
	v_lshlrev_b32_e32 v4, 6, v176
	v_mov_b32_e32 v5, 0
	v_writelane_b32 v240, s1, 34
	s_add_u32 s4, s30, 0x50000
	v_lshl_add_u64 v[2:3], s[30:31], 0, v[4:5]
	s_mov_b64 s[0:1], 0x60000
	v_lshlrev_b32_e32 v4, 2, v176
	s_addc_u32 s5, s31, 0
	s_lshl_b32 s2, s9, 9
	v_lshl_add_u64 v[2:3], v[2:3], 0, s[0:1]
	v_lshl_add_u64 v[4:5], s[30:31], 0, v[4:5]
	s_mov_b64 s[0:1], 0xe0000
	v_lshl_add_u64 v[4:5], v[4:5], 0, s[0:1]
	s_lshl_b32 s0, s9, 10
	s_ashr_i32 s3, s2, 31
	v_writelane_b32 v240, s0, 35
	s_lshl_b64 s[0:1], s[2:3], 2
	v_writelane_b32 v240, s0, 36
	v_lshlrev_b32_e32 v1, 1, v204
	v_lshl_add_u32 v6, s8, 10, v1
	s_cmp_eq_u32 s9, 0x100
	s_cselect_b32 s78, 0x3c000, 0
	v_subrev_u32_e32 v6, s78, v6
	v_writelane_b32 v240, s1, 37
	s_mov_b32 s0, s2
	v_writelane_b32 v240, s0, 38
	v_ashrrev_i32_e32 v1, 31, v0
	s_lshl_b64 s[46:47], s[2:3], 6
	v_writelane_b32 v240, s1, 39
	s_mov_b32 s78, 0
	s_mov_b32 s88, 0
	s_mov_b32 s94, 0x54442d18
	s_mov_b32 s0, 0
	s_mov_b32 s10, 0
	s_mov_b32 s6, 0
	s_mov_b32 s68, 0
	s_mov_b32 s72, 0
	s_mov_b32 s42, 0
	s_mov_b32 s2, 0
	s_mov_b32 s34, 0
	s_mov_b32 s38, 0
	s_mov_b32 s74, 0
	s_mov_b32 s76, 0
	s_mov_b32 s80, 0
	s_mov_b32 s82, 0
	s_mov_b32 s84, 0
	s_mov_b32 s86, 0
	s_mov_b32 s90, 0
	v_lshlrev_b64 v[8:9], 2, v[0:1]
	v_lshlrev_b64 v[10:11], 6, v[0:1]
	s_mov_b64 s[48:49], 0
	v_mov_b32_e32 v1, 0x7f800000
	s_mov_b32 s79, 0x40180000
	s_mov_b32 s89, 0x40280000
	s_mov_b32 s95, 0x401921fb
	s_mov_b32 s97, 0xc01921fb
	s_mov_b32 s1, 0xc05b8000
	s_mov_b32 s11, 0xc0608000
	s_mov_b32 s7, 0xc0638000
	s_mov_b32 s69, 0xc066c000
	s_mov_b32 s73, 0xc06a4000
	s_mov_b32 s43, 0xc0756000
	s_mov_b32 s3, 0xc077c000
	s_mov_b32 s35, 0xc07a4000
	s_movk_i32 s33, 0x1ff
	s_movk_i32 s92, 0xffe
	v_mov_b32_e32 v22, 0x7c00
	v_mov_b32_e32 v23, 0x7e00
	s_movk_i32 s93, 0x40f
	s_mov_b32 s70, 0x8000
	s_mov_b32 s71, 0x5040100
	s_mov_b32 s39, 0xc07ce000
	s_mov_b32 s75, 0xc07fa000
	s_mov_b32 s77, 0xc0814000
	s_mov_b32 s81, 0xc082c000
	s_mov_b32 s83, 0xc0845000
	s_mov_b32 s85, 0xc085f000
	s_mov_b32 s87, 0xc087a000
	s_mov_b32 s91, 0xc0896000
